# v57 with the redundant second workgroup barrier at each mixer producer-unit end removed (nothing between the two barriers but already-satisfied waits)
# baseline (speedup 1.0000x reference)
; __device__ __forceinline__ unsigned xb_add(unsigned* p, unsigned v) { return __hip_atomic_fetch_add(p, v, __ATOMIC_RELAXED, __HIP_MEMORY_SCOPE_AGENT); }
; template <int MODE> __device__ __forceinline__ void unit(const Job& J, char* shm) {
;     ...
;     asm volatile("s_waitcnt vmcnt(0) lgkmcnt(0)\n\ts_barrier" ::: "memory");
; __device__ __forceinline__ void publish_cnt(unsigned* c) {
;     asm volatile("s_waitcnt vmcnt(0)" ::: "memory");
;     __syncthreads();
;     if (threadIdx.x == 0) (void)xb_add(c, 1u);
; }
.Lpf_skip_1:
	s_mov_b32 s101, 1
	s_waitcnt vmcnt(0) lgkmcnt(0)
	s_barrier
	s_waitcnt vmcnt(0)
	s_waitcnt lgkmcnt(0)
	s_and_saveexec_b64 s[0:1], s[62:63]
	s_xor_b64 s[0:1], exec, s[0:1]
	s_cbranch_execz .LBB0_554
	s_mul_i32 s86, s2, 0x210
	s_lshl_b64 s[2:3], s[86:87], 2
	s_add_u32 s2, s53, s2
	s_addc_u32 s3, s54, s3
	v_mov_b64_e32 v[2:3], s[2:3]
	flat_atomic_add v[2:3], v218 offset:2048

; __device__ __forceinline__ unsigned xb_add(unsigned* p, unsigned v) { return __hip_atomic_fetch_add(p, v, __ATOMIC_RELAXED, __HIP_MEMORY_SCOPE_AGENT); }
; __device__ __forceinline__ void publish_cnt(unsigned* c) {
;     asm volatile("s_waitcnt vmcnt(0)" ::: "memory");
;     __syncthreads();
;     if (threadIdx.x == 0) (void)xb_add(c, 1u);
; }
; __device__ __forceinline__ void sg_unit(const Params& P, int l, int chunk, char* shm, float* ssb) {
;     ...
;     asm volatile("s_waitcnt vmcnt(0) lgkmcnt(0)\n\ts_barrier" ::: "memory");
.Lpf_skip_2:
	s_mov_b32 s101, 1
	s_waitcnt vmcnt(0) lgkmcnt(0)
	s_barrier
	s_waitcnt vmcnt(0)
	s_waitcnt lgkmcnt(0)
	s_and_saveexec_b64 s[0:1], s[62:63]
	s_xor_b64 s[0:1], exec, s[0:1]
	s_cbranch_execz .LBB0_578
	s_lshl_b32 s2, s3, 3
	s_and_b32 s86, s2, 0x7ffffff0
	s_lshl_b64 s[2:3], s[86:87], 2
	s_add_u32 s2, s53, s2
	s_addc_u32 s3, s54, s3
	v_mov_b64_e32 v[2:3], s[2:3]
	flat_atomic_add v[2:3], v218

; __device__ __forceinline__ unsigned xb_add(unsigned* p, unsigned v) { return __hip_atomic_fetch_add(p, v, __ATOMIC_RELAXED, __HIP_MEMORY_SCOPE_AGENT); }
;     ...
;     asm volatile("s_waitcnt vmcnt(0) lgkmcnt(0)\n\ts_barrier" ::: "memory");
; __device__ __forceinline__ void publish_cnt(unsigned* c) {
;     asm volatile("s_waitcnt vmcnt(0)" ::: "memory");
;     __syncthreads();
;     if (threadIdx.x == 0) (void)xb_add(c, 1u);
; }
.Lpf_skip_3:
	s_mov_b32 s101, 1
	s_waitcnt vmcnt(0) lgkmcnt(0)
	s_barrier
	s_waitcnt vmcnt(0)
	s_waitcnt lgkmcnt(0)
	s_and_saveexec_b64 s[0:1], s[62:63]
	s_xor_b64 s[0:1], exec, s[0:1]
	s_cbranch_execz .LBB0_872
	v_readlane_b32 s2, v252, 28
	v_readlane_b32 s3, v252, 29
	s_and_b64 s[2:3], s[2:3], exec
	s_cselect_b32 s2, 33, 0
	v_readlane_b32 s3, v252, 27
	s_add_i32 s2, s2, s3
	s_lshl_b32 s2, s2, 6
	s_add_u32 s2, s53, s2
	s_addc_u32 s3, s54, 0
	v_mov_b64_e32 v[2:3], s[2:3]
	flat_atomic_add v[2:3], v218

; __device__ __forceinline__ unsigned xb_add(unsigned* p, unsigned v) { return __hip_atomic_fetch_add(p, v, __ATOMIC_RELAXED, __HIP_MEMORY_SCOPE_AGENT); }
;     ...
;     asm volatile("s_waitcnt vmcnt(0) lgkmcnt(0)\n\ts_barrier" ::: "memory");
; __device__ __forceinline__ void publish_cnt(unsigned* c) {
;     asm volatile("s_waitcnt vmcnt(0)" ::: "memory");
;     __syncthreads();
;     if (threadIdx.x == 0) (void)xb_add(c, 1u);
; }
.Lpf_skip_4:
	s_mov_b32 s101, 1
	s_waitcnt vmcnt(0) lgkmcnt(0)
	s_barrier
	s_waitcnt vmcnt(0)
	s_waitcnt lgkmcnt(0)
	s_and_saveexec_b64 s[0:1], s[62:63]
	s_xor_b64 s[0:1], exec, s[0:1]
	s_cbranch_execz .LBB0_438
	s_mul_i32 s2, s18, 33
	s_add_i32 s2, s2, s3
	s_lshl_b32 s2, s2, 4
	s_ashr_i32 s3, s2, 31
	s_lshl_b64 s[2:3], s[2:3], 2
	s_add_u32 s2, s53, s2
	s_addc_u32 s3, s54, s3
	v_mov_b64_e32 v[2:3], s[2:3]
	flat_atomic_add v[2:3], v218
	s_branch .LBB0_438
